# grid barrier: waiting blocks poll the top-level generation word directly instead of the per-XCD word (one fewer hop)
# speedup vs baseline: 1.0846x; 1.0058x over previous
.LBB0_478:
	s_or_b64 exec, exec, s[2:3]
	v_cvt_f32_u32_e32 v4, v2
	s_waitcnt vmcnt(0)
	v_readfirstlane_b32 s2, v3
	v_sub_u32_e32 v3, 0, v2
	v_rcp_iflag_f32_e32 v4, v4
	v_add_u32_e32 v5, s2, v1
	v_mul_f32_e32 v4, 0x4f7ffffe, v4
	v_cvt_u32_f32_e32 v4, v4
	v_mul_lo_u32 v1, v3, v4
	v_mul_hi_u32 v1, v4, v1
	v_add_u32_e32 v1, v4, v1
	v_mul_hi_u32 v1, v5, v1
	v_mul_lo_u32 v3, v1, v2
	v_sub_u32_e32 v3, v5, v3
	v_add_u32_e32 v4, 1, v1
	v_cmp_ge_u32_e32 vcc, v3, v2
	s_nop 1
	v_cndmask_b32_e32 v1, v1, v4, vcc
	v_sub_u32_e32 v4, v3, v2
	v_cndmask_b32_e32 v3, v3, v4, vcc
	v_add_u32_e32 v4, 1, v1
	v_cmp_ge_u32_e32 vcc, v3, v2
	v_add_u32_e32 v3, 1, v5
	s_nop 0
	v_cndmask_b32_e32 v1, v1, v4, vcc
	v_mul_lo_u32 v4, v2, v1
	v_add_u32_e32 v2, v4, v2
	v_cmp_ne_u32_e32 vcc, v3, v2
	s_and_saveexec_b64 s[2:3], vcc
	s_xor_b64 s[2:3], exec, s[2:3]
	s_cbranch_execz .LBB0_492
	v_readlane_b32 s4, v254, 19
	s_waitcnt lgkmcnt(0)
	v_mov_b32_e32 v0, 0
	v_readlane_b32 s5, v254, 20
	s_nop 4
	global_load_dword v2, v0, s[4:5] sc1
	s_waitcnt vmcnt(0)
	v_cmp_eq_u32_e32 vcc, v2, v1
	s_and_saveexec_b64 s[6:7], vcc
	s_cbranch_execz .LBB0_491
	s_mov_b32 s4, 1
	s_mov_b64 s[8:9], 0
	s_branch .LBB0_482

.LBB0_486:
	v_readlane_b32 s12, v254, 19
	v_readlane_b32 s13, v254, 20
	s_add_i32 s4, s4, 1
	s_mov_b64 s[14:15], -1
	s_nop 2
	global_load_dword v2, v0, s[12:13] sc1
	s_waitcnt vmcnt(0)
	v_cmp_ne_u32_e32 vcc, v2, v1
	s_orn2_b64 s[12:13], vcc, exec
	s_branch .LBB0_481

.LBB0_573:
	s_or_b64 exec, exec, s[2:3]
	v_cvt_f32_u32_e32 v4, v2
	s_waitcnt vmcnt(0)
	v_readfirstlane_b32 s2, v3
	v_sub_u32_e32 v3, 0, v2
	v_rcp_iflag_f32_e32 v4, v4
	v_add_u32_e32 v5, s2, v1
	v_mul_f32_e32 v4, 0x4f7ffffe, v4
	v_cvt_u32_f32_e32 v4, v4
	v_mul_lo_u32 v1, v3, v4
	v_mul_hi_u32 v1, v4, v1
	v_add_u32_e32 v1, v4, v1
	v_mul_hi_u32 v1, v5, v1
	v_mul_lo_u32 v3, v1, v2
	v_sub_u32_e32 v3, v5, v3
	v_add_u32_e32 v4, 1, v1
	v_cmp_ge_u32_e32 vcc, v3, v2
	s_nop 1
	v_cndmask_b32_e32 v1, v1, v4, vcc
	v_sub_u32_e32 v4, v3, v2
	v_cndmask_b32_e32 v3, v3, v4, vcc
	v_add_u32_e32 v4, 1, v1
	v_cmp_ge_u32_e32 vcc, v3, v2
	v_add_u32_e32 v3, 1, v5
	s_nop 0
	v_cndmask_b32_e32 v1, v1, v4, vcc
	v_mul_lo_u32 v4, v2, v1
	v_add_u32_e32 v2, v4, v2
	v_cmp_ne_u32_e32 vcc, v3, v2
	s_and_saveexec_b64 s[2:3], vcc
	s_xor_b64 s[2:3], exec, s[2:3]
	s_cbranch_execz .LBB0_587
	v_readlane_b32 s4, v254, 19
	v_readlane_b32 s5, v254, 20
	s_waitcnt lgkmcnt(0)
	s_nop 3
	global_load_dword v0, v65, s[4:5] sc1
	s_waitcnt vmcnt(0)
	v_cmp_eq_u32_e32 vcc, v0, v1
	s_and_saveexec_b64 s[8:9], vcc
	s_cbranch_execz .LBB0_586
	s_mov_b32 s4, 1
	s_mov_b64 s[10:11], 0
	s_branch .LBB0_577

.LBB0_581:
	v_readlane_b32 s6, v254, 19
	v_readlane_b32 s7, v254, 20
	s_add_i32 s4, s4, 1
	s_mov_b64 s[24:25], -1
	s_nop 2
	global_load_dword v0, v65, s[6:7] sc1
	s_waitcnt vmcnt(0)
	v_cmp_ne_u32_e32 vcc, v0, v1
	s_orn2_b64 s[20:21], vcc, exec
	s_branch .LBB0_576

.LBB0_1104:
	s_or_b64 exec, exec, s[8:9]
	v_cvt_f32_u32_e32 v4, v2
	s_waitcnt vmcnt(0)
	v_readfirstlane_b32 s2, v3
	v_sub_u32_e32 v3, 0, v2
	v_rcp_iflag_f32_e32 v4, v4
	v_add_u32_e32 v5, s2, v1
	v_mul_f32_e32 v4, 0x4f7ffffe, v4
	v_cvt_u32_f32_e32 v4, v4
	v_mul_lo_u32 v1, v3, v4
	v_mul_hi_u32 v1, v4, v1
	v_add_u32_e32 v1, v4, v1
	v_mul_hi_u32 v1, v5, v1
	v_mul_lo_u32 v3, v1, v2
	v_sub_u32_e32 v3, v5, v3
	v_add_u32_e32 v4, 1, v1
	v_cmp_ge_u32_e32 vcc, v3, v2
	s_nop 1
	v_cndmask_b32_e32 v1, v1, v4, vcc
	v_sub_u32_e32 v4, v3, v2
	v_cndmask_b32_e32 v3, v3, v4, vcc
	v_add_u32_e32 v4, 1, v1
	v_cmp_ge_u32_e32 vcc, v3, v2
	v_add_u32_e32 v3, 1, v5
	s_nop 0
	v_cndmask_b32_e32 v1, v1, v4, vcc
	v_mul_lo_u32 v4, v2, v1
	v_add_u32_e32 v2, v4, v2
	v_cmp_ne_u32_e32 vcc, v3, v2
	s_and_saveexec_b64 s[2:3], vcc
	s_xor_b64 s[8:9], exec, s[2:3]
	s_cbranch_execz .LBB0_1118
	v_readlane_b32 s2, v254, 19
	v_readlane_b32 s3, v254, 20
	s_waitcnt lgkmcnt(0)
	s_nop 3
	global_load_dword v0, v65, s[2:3] sc1
	s_waitcnt vmcnt(0)
	v_cmp_eq_u32_e32 vcc, v0, v1
	s_and_saveexec_b64 s[10:11], vcc
	s_cbranch_execz .LBB0_1117
	s_mov_b32 s2, 1
	s_mov_b64 s[18:19], 0
	s_branch .LBB0_1108

.LBB0_1112:
	v_readlane_b32 s4, v254, 19
	v_readlane_b32 s5, v254, 20
	s_add_i32 s2, s2, 1
	s_mov_b64 s[30:31], -1
	s_nop 2
	global_load_dword v0, v65, s[4:5] sc1
	s_waitcnt vmcnt(0)
	v_cmp_ne_u32_e32 vcc, v0, v1
	s_orn2_b64 s[24:25], vcc, exec
	s_branch .LBB0_1107
